# P+2 merge-first workgroups chosen by blockIdx bit 3 so both kinds of work share every XCD (was bit 0, which split by XCD)
# baseline (speedup 1.0000x reference)
.Lp2_again:
	s_mov_b64 s[0:1], 0
	s_add_u32 s46, s80, s0
	s_addc_u32 s47, s81, s1
	v_readlane_b32 s62, v254, 0
	v_mov_b32_e32 v149, v230
	s_cmpk_lt_i32 s62, 0x200
	s_cbranch_scc0 .LBB0_450
	s_cmp_lg_u32 s100, 0
	s_cbranch_scc1 .Lp2_chunk
	s_bitcmp1_b32 s62, 3
	s_cbranch_scc0 .Lp2_chunk
	s_mov_b32 s100, 1
	s_branch .LBB0_450
